# norm phases: context-row per-column parameters (gain/scale/shift) loaded once up front instead of 12 serialised round trips
# speedup vs baseline: 1.0091x; 1.0003x over previous
.LBB0_535:
	s_or_b64 exec, exec, s[16:17]
	s_or_b64 s[0:1], s[50:51], s[14:15]
	s_and_b64 s[0:1], s[0:1], exec
	s_movk_i32 s0, 0x4100
	s_cselect_b32 s18, s0, 0x4000
	s_waitcnt vmcnt(0)
	v_add_u32_e32 v66, 0x4000, v84
	v_cmp_gt_i32_e32 vcc, s18, v66
	s_and_saveexec_b64 s[0:1], vcc
	v_readlane_b32 s56, v255, 11
	s_movk_i32 s57, 0x1700
	s_cbranch_execz .LBB0_548
	s_cmp_gt_i32 s10, 9
	s_cselect_b32 s16, 11, 0
	s_and_b64 s[2:3], s[14:15], exec
	s_cselect_b32 s19, s16, 4
	s_add_u32 s2, s12, 0x6000
	v_sub_co_u32_e64 v2, s[14:15], s19, 1
	s_addc_u32 s3, s13, 0
	s_xor_b64 s[14:15], s[14:15], -1
	s_add_u32 s12, s12, 0x7000
	v_readlane_b32 s16, v252, 5
	s_addc_u32 s13, s13, 0
	v_mov_b32_e32 v93, v1
	v_mov_b32_e32 v91, v1
	v_mov_b32_e32 v89, v1
	v_readlane_b32 s60, v254, 42
	v_readlane_b32 s17, v252, 6
	v_lshl_add_u64 v[72:73], s[2:3], 0, v[0:1]
	v_lshl_add_u64 v[76:77], s[2:3], 0, v[92:93]
	v_lshl_add_u64 v[78:79], s[12:13], 0, v[90:91]
	v_lshl_add_u64 v[80:81], s[2:3], 0, v[90:91]
	v_lshl_add_u64 v[90:91], s[12:13], 0, v[88:89]
	v_lshl_add_u64 v[88:89], s[2:3], 0, v[88:89]
	s_and_b64 s[2:3], s[38:39], exec
	v_readlane_b32 s64, v254, 46
	v_readlane_b32 s65, v254, 47
	v_lshl_add_u64 v[70:71], s[12:13], 0, v[0:1]
	v_lshl_add_u64 v[74:75], s[12:13], 0, v[92:93]
	s_cselect_b32 s3, s65, s17
	s_cselect_b32 s2, s64, s16
	v_readlane_b32 s12, v252, 30
	v_lshl_add_u64 v[92:93], s[2:3], 0, v[0:1]
	v_readlane_b32 s13, v252, 31
	v_readlane_b32 s2, v252, 20
	v_lshl_add_u64 v[68:69], s[16:17], 0, v[0:1]
	v_lshl_add_u64 v[94:95], s[12:13], 0, v[0:1]
	v_mov_b32_e32 v87, v1
	v_readlane_b32 s3, v252, 21
	v_lshlrev_b32_e32 v0, 4, v116
	v_readfirstlane_b32 s22, v2
	v_lshl_add_u64 v[86:87], s[2:3], 0, v[86:87]
	v_lshl_add_u64 v[96:97], s[12:13], 0, v[0:1]
	s_mov_b64 s[12:13], 0
	v_readlane_b32 s61, v254, 43
	v_readlane_b32 s62, v254, 44
	v_readlane_b32 s63, v254, 45
	v_readlane_b32 s66, v254, 48
	v_readlane_b32 s67, v254, 49
	v_readlane_b32 s68, v254, 50
	v_readlane_b32 s69, v254, 51
	v_readlane_b32 s70, v254, 52
	v_readlane_b32 s71, v254, 53
	v_readlane_b32 s72, v254, 54
	v_readlane_b32 s73, v254, 55
	v_readlane_b32 s74, v254, 56
	v_readlane_b32 s75, v254, 57
	global_load_dwordx4 v[126:129], v[82:83], off
	global_load_dwordx4 v[130:133], v[70:71], off
	global_load_dwordx4 v[134:137], v[72:73], off
	global_load_dwordx4 v[138:141], v[82:83], off offset:1024
	global_load_dwordx4 v[142:145], v[74:75], off
	global_load_dwordx4 v[146:149], v[76:77], off
	global_load_dwordx4 v[150:153], v[82:83], off offset:2048
	global_load_dwordx4 v[154:157], v[78:79], off
	global_load_dwordx4 v[158:161], v[80:81], off
	global_load_dwordx4 v[162:165], v[82:83], off offset:3072
	global_load_dwordx4 v[166:169], v[90:91], off
	global_load_dwordx4 v[170:173], v[88:89], off
	s_branch .LBB0_539

.LBB0_538:
	s_waitcnt vmcnt(0)
	v_mov_b32_e32 v20, v11
	v_mov_b32_e32 v21, v15
	v_mov_b32_e32 v18, v10
	v_mov_b32_e32 v19, v14
	v_pk_mul_f32 v[20:21], v[20:21], v[20:21]
	v_mov_b32_e32 v22, v3
	v_pk_fma_f32 v[18:19], v[18:19], v[18:19], v[20:21]
	v_mov_b32_e32 v20, v12
	v_mov_b32_e32 v21, v16
	v_pk_fma_f32 v[18:19], v[20:21], v[20:21], v[18:19]
	v_mov_b32_e32 v20, v13
	v_mov_b32_e32 v21, v17
	v_mov_b32_e32 v23, v7
	v_pk_fma_f32 v[18:19], v[20:21], v[20:21], v[18:19]
	v_mov_b32_e32 v20, v2
	v_mov_b32_e32 v21, v6
	v_pk_mul_f32 v[22:23], v[22:23], v[22:23]
	v_add_f32_e32 v0, v18, v19
	v_pk_fma_f32 v[20:21], v[20:21], v[20:21], v[22:23]
	v_mov_b32_e32 v22, v4
	v_mov_b32_e32 v23, v8
	v_pk_fma_f32 v[20:21], v[22:23], v[22:23], v[20:21]
	v_mov_b32_e32 v22, v5
	v_mov_b32_e32 v23, v9
	v_pk_fma_f32 v[20:21], v[22:23], v[22:23], v[20:21]
	v_cmp_lt_i32_e32 vcc, v209, v208
	v_add_f32_e32 v0, v21, v0
	v_add_f32_e32 v0, v20, v0
	v_cndmask_b32_e32 v18, v207, v209, vcc
	v_lshlrev_b32_e32 v18, 2, v18
	ds_bpermute_b32 v18, v18, v0
	v_cmp_lt_i32_e32 vcc, v210, v208
	v_add_u32_e32 v84, s33, v84
	s_waitcnt lgkmcnt(0)
	v_add_f32_e32 v0, v0, v18
	v_cndmask_b32_e32 v18, v207, v210, vcc
	v_lshlrev_b32_e32 v18, 2, v18
	ds_bpermute_b32 v18, v18, v0
	v_cmp_lt_i32_e32 vcc, v211, v208
	s_waitcnt lgkmcnt(0)
	v_add_f32_e32 v0, v0, v18
	v_cndmask_b32_e32 v18, v207, v211, vcc
	v_lshlrev_b32_e32 v18, 2, v18
	ds_bpermute_b32 v18, v18, v0
	v_cmp_lt_i32_e32 vcc, v212, v208
	s_waitcnt lgkmcnt(0)
	v_add_f32_e32 v0, v0, v18
	v_cndmask_b32_e32 v18, v207, v212, vcc
	v_lshlrev_b32_e32 v18, 2, v18
	ds_bpermute_b32 v18, v18, v0
	v_cmp_lt_i32_e32 vcc, v213, v208
	s_waitcnt lgkmcnt(0)
	v_add_f32_e32 v0, v0, v18
	v_cndmask_b32_e32 v18, v207, v213, vcc
	v_lshlrev_b32_e32 v18, 2, v18
	ds_bpermute_b32 v18, v18, v0
	v_cmp_lt_i32_e32 vcc, v214, v208
	s_waitcnt lgkmcnt(0)
	v_add_f32_e32 v0, v0, v18
	v_cndmask_b32_e32 v18, v207, v214, vcc
	v_lshlrev_b32_e32 v18, 2, v18
	ds_bpermute_b32 v18, v18, v0
	s_waitcnt lgkmcnt(0)
	v_add_f32_e32 v0, v0, v18
	v_fmamk_f32 v0, v0, 0x3a800000, v203
	v_cmp_gt_f32_e32 vcc, s28, v0
	v_mul_f32_e32 v18, 0x4b800000, v0
	s_nop 0
	v_cndmask_b32_e32 v0, v0, v18, vcc
	v_rsq_f32_e32 v0, v0
	s_nop 0
	v_mul_f32_e32 v18, 0x45800000, v0
	v_cndmask_b32_e32 v0, v0, v18, vcc
	v_pk_mul_f32 v[16:17], v[16:17], v[0:1] op_sel_hi:[1,0]
	v_pk_mul_f32 v[14:15], v[14:15], v[0:1] op_sel_hi:[1,0]
	v_cmp_gt_i32_e32 vcc, s37, v66
	v_pk_mul_f32 v[20:21], v[126:127], v[14:15]
	v_pk_mul_f32 v[22:23], v[128:129], v[16:17]
	v_cndmask_b32_e64 v18, 3, 1, vcc
	v_add_u32_e32 v18, v18, v66
	v_ashrrev_i32_e32 v19, 31, v18
	v_lshlrev_b64 v[18:19], 11, v[18:19]
	v_add_u32_e32 v66, s33, v66
	v_cmp_le_i32_e32 vcc, s18, v66
	s_or_b64 s[12:13], vcc, s[12:13]
	v_pk_add_f32 v[24:25], v[132:133], 1.0 op_sel_hi:[1,0]
	v_pk_add_f32 v[26:27], v[130:131], 1.0 op_sel_hi:[1,0]
	v_pk_fma_f32 v[16:17], v[24:25], v[22:23], v[136:137]
	v_pk_fma_f32 v[14:15], v[26:27], v[20:21], v[134:135]
	s_nop 0
	v_cvt_pk_bf16_f32 v14, v14, v15
	v_cvt_pk_bf16_f32 v15, v16, v17
	v_lshl_add_u64 v[16:17], v[86:87], 0, v[18:19]
	global_store_dwordx2 v[16:17], v[14:15], off
	v_pk_mul_f32 v[14:15], v[12:13], v[0:1] op_sel_hi:[1,0]
	v_pk_mul_f32 v[18:19], v[10:11], v[0:1] op_sel_hi:[1,0]
	v_pk_mul_f32 v[18:19], v[138:139], v[18:19]
	v_pk_mul_f32 v[14:15], v[140:141], v[14:15]
	v_pk_add_f32 v[20:21], v[144:145], 1.0 op_sel_hi:[1,0]
	v_pk_add_f32 v[22:23], v[142:143], 1.0 op_sel_hi:[1,0]
	v_pk_fma_f32 v[10:11], v[22:23], v[18:19], v[146:147]
	v_pk_fma_f32 v[12:13], v[20:21], v[14:15], v[148:149]
	v_cvt_pk_bf16_f32 v10, v10, v11
	s_nop 0
	v_cvt_pk_bf16_f32 v11, v12, v13
	global_store_dwordx2 v[16:17], v[10:11], off offset:512
	v_pk_mul_f32 v[10:11], v[8:9], v[0:1] op_sel_hi:[1,0]
	v_pk_mul_f32 v[12:13], v[6:7], v[0:1] op_sel_hi:[1,0]
	v_pk_mul_f32 v[12:13], v[150:151], v[12:13]
	v_pk_mul_f32 v[10:11], v[152:153], v[10:11]
	v_pk_add_f32 v[14:15], v[156:157], 1.0 op_sel_hi:[1,0]
	v_pk_add_f32 v[18:19], v[154:155], 1.0 op_sel_hi:[1,0]
	v_pk_fma_f32 v[6:7], v[18:19], v[12:13], v[158:159]
	v_pk_fma_f32 v[8:9], v[14:15], v[10:11], v[160:161]
	v_cvt_pk_bf16_f32 v6, v6, v7
	s_nop 0
	v_cvt_pk_bf16_f32 v7, v8, v9
	global_store_dwordx2 v[16:17], v[6:7], off offset:1024
	v_pk_mul_f32 v[6:7], v[4:5], v[0:1] op_sel_hi:[1,0]
	v_pk_mul_f32 v[8:9], v[2:3], v[0:1] op_sel_hi:[1,0]
	v_pk_mul_f32 v[8:9], v[8:9], v[162:163]
	v_pk_mul_f32 v[6:7], v[6:7], v[164:165]
	v_pk_add_f32 v[10:11], v[168:169], 1.0 op_sel_hi:[1,0]
	v_pk_add_f32 v[12:13], v[166:167], 1.0 op_sel_hi:[1,0]
	v_pk_fma_f32 v[2:3], v[8:9], v[12:13], v[170:171]
	v_pk_fma_f32 v[4:5], v[6:7], v[10:11], v[172:173]
	v_cvt_pk_bf16_f32 v2, v2, v3
	s_nop 0
	v_cvt_pk_bf16_f32 v3, v4, v5
	global_store_dwordx2 v[16:17], v[2:3], off offset:1536
	s_andn2_b64 exec, exec, s[12:13]
	s_cbranch_execz .LBB0_548
